# hazard-slot filling: the m0 -> LDS-DMA wait state in the attention steady loop is supplied by a useful VALU instruction (address add / row-max op) instead of s_nop 0: 4 issue slots fewer per loop iter
# baseline (speedup 1.0000x reference)
.LBB0_148:
	v_add_u32_e32 v168, s6, v221
	ds_read_b64_tr_b16 v[164:165], v168 offset:24576
	ds_read_b64_tr_b16 v[166:167], v168 offset:25088
	v_mfma_f32_32x32x16_bf16 v[64:79], v[156:159], v[116:119], v[64:79]
	v_add_f32_e32 v104, v80, v81
	v_add_f32_e32 v104, v82, v104
	v_add_f32_e32 v104, v83, v104
	v_add_f32_e32 v104, v84, v104
	v_add_f32_e32 v104, v85, v104
	v_cvt_pk_bf16_f32 v124, v80, v81
	v_cvt_pk_bf16_f32 v125, v82, v83
	ds_read_b64_tr_b16 v[160:161], v168 offset:28672
	ds_read_b64_tr_b16 v[162:163], v168 offset:29184
	v_mfma_f32_32x32x16_bf16 v[48:63], v[152:155], v[116:119], v[48:63]
	v_add_f32_e32 v80, v86, v104
	v_add_f32_e32 v80, v87, v80
	v_add_f32_e32 v80, v88, v80
	v_add_f32_e32 v80, v89, v80
	v_cvt_pk_bf16_f32 v126, v84, v85
	v_cvt_pk_bf16_f32 v127, v86, v87
	ds_read_b64_tr_b16 v[152:153], v168 offset:25600
	ds_read_b64_tr_b16 v[154:155], v168 offset:26112
	v_mfma_f32_32x32x16_bf16 v[64:79], v[148:151], v[108:111], v[64:79]
	v_add_f32_e32 v80, v90, v80
	v_add_f32_e32 v80, v91, v80
	v_add_f32_e32 v80, v92, v80
	v_add_f32_e32 v80, v93, v80
	v_cvt_pk_bf16_f32 v120, v88, v89
	v_cvt_pk_bf16_f32 v121, v90, v91
	ds_read_b64_tr_b16 v[148:149], v168 offset:29696
	ds_read_b64_tr_b16 v[150:151], v168 offset:30208
	v_mfma_f32_32x32x16_bf16 v[48:63], v[144:147], v[108:111], v[48:63]
	v_add_f32_e32 v80, v94, v80
	v_add_f32_e32 v80, v95, v80
	v_add_f32_e32 v80, v32, v80
	v_add_f32_e32 v80, v33, v80
	v_cvt_pk_bf16_f32 v122, v92, v93
	v_cvt_pk_bf16_f32 v123, v94, v95
	ds_read_b64_tr_b16 v[156:157], v168 offset:26624
	ds_read_b64_tr_b16 v[158:159], v168 offset:27136
	v_mfma_f32_32x32x16_bf16 v[64:79], v[140:143], v[100:103], v[64:79]
	v_add_f32_e32 v80, v34, v80
	v_add_f32_e32 v80, v35, v80
	v_add_f32_e32 v80, v36, v80
	v_add_f32_e32 v80, v37, v80
	v_cvt_pk_bf16_f32 v112, v32, v33
	v_cvt_pk_bf16_f32 v113, v34, v35
	ds_read_b64_tr_b16 v[144:145], v168 offset:30720
	ds_read_b64_tr_b16 v[146:147], v168 offset:31232
	v_mfma_f32_32x32x16_bf16 v[48:63], v[132:135], v[100:103], v[48:63]
	v_add_f32_e32 v32, v38, v80
	v_add_f32_e32 v32, v39, v32
	v_add_f32_e32 v32, v40, v32
	v_add_f32_e32 v32, v41, v32
	v_cvt_pk_bf16_f32 v114, v36, v37
	v_cvt_pk_bf16_f32 v115, v38, v39
	ds_read_b64_tr_b16 v[140:141], v168 offset:27648
	ds_read_b64_tr_b16 v[142:143], v168 offset:28160
	v_mfma_f32_32x32x16_bf16 v[64:79], v[136:139], v[96:99], v[64:79]
	v_add_f32_e32 v32, v42, v32
	v_add_f32_e32 v32, v43, v32
	v_add_f32_e32 v32, v44, v32
	v_add_f32_e32 v32, v45, v32
	v_cvt_pk_bf16_f32 v104, v40, v41
	v_cvt_pk_bf16_f32 v105, v42, v43
	ds_read_b64_tr_b16 v[132:133], v168 offset:31744
	ds_read_b64_tr_b16 v[134:135], v168 offset:32256
	v_mfma_f32_32x32x16_bf16 v[48:63], v[128:131], v[96:99], v[48:63]
	v_add_f32_e32 v32, v46, v32
	v_add_f32_e32 v32, v47, v32
	v_add_f32_e32 v34, 0, v32
	v_cvt_pk_bf16_f32 v106, v44, v45
	v_cvt_pk_bf16_f32 v107, v46, v47
	s_add_i32 m0, s41, s18
	v_lshl_add_u64 v[32:33], v[178:179], 0, s[90:91]
	global_load_lds_dwordx4 v[32:33], off
	s_add_i32 m0, s28, s19
	v_lshl_add_u64 v[32:33], v[176:177], 0, s[90:91]
	global_load_lds_dwordx4 v[32:33], off
	v_max_f32_e32 v32, v64, v65
	v_max3_f32 v33, v66, v67, v49
	v_max3_f32 v32, v32, v48, v50
	v_max3_f32 v32, v32, v51, v68
	v_max3_f32 v33, v33, v70, v71
	v_max3_f32 v32, v32, v69, v52
	v_max3_f32 v33, v33, v54, v55
	v_max3_f32 v32, v32, v53, v72
	v_max3_f32 v33, v33, v74, v75
	v_max3_f32 v32, v32, v73, v56
	v_max3_f32 v33, v33, v58, v59
	v_max3_f32 v32, v32, v57, v76
	v_max3_f32 v33, v33, v78, v79
	v_max3_f32 v32, v32, v77, v60
	v_max3_f32 v33, v33, v62, v63
	v_max3_f32 v32, v32, v61, v33
	v_mov_b32_e32 v33, v32
	s_nop 1
	v_permlane32_swap_b32_e32 v32, v33
	v_max_f32_e32 v32, v32, v33
	v_cmp_lt_f32_e32 vcc, s47, v32
	s_cmp_lg_u64 vcc, 0
	v_add_f32_e32 v181, v222, v34
	s_cselect_b64 s[6:7], -1, 0
	s_cbranch_vccnz .LBB0_156

.LBB0_151:
	s_add_i32 s6, s28, 0x2000
	s_cmpk_lg_i32 s28, 0x4000
	s_cselect_b32 s22, s6, 0
	v_add_u32_e32 v182, s41, v221
	ds_read_b64_tr_b16 v[144:145], v182 offset:24576
	ds_read_b64_tr_b16 v[146:147], v182 offset:25088
	v_mfma_f32_32x32x16_bf16 v[80:95], v[168:171], v[116:119], v[80:95]
	v_add_f32_e32 v104, v64, v65
	v_add_f32_e32 v104, v66, v104
	v_add_f32_e32 v104, v67, v104
	v_add_f32_e32 v104, v68, v104
	v_add_f32_e32 v104, v69, v104
	v_cvt_pk_bf16_f32 v124, v64, v65
	v_cvt_pk_bf16_f32 v125, v66, v67
	ds_read_b64_tr_b16 v[140:141], v182 offset:28672
	ds_read_b64_tr_b16 v[142:143], v182 offset:29184
	v_mfma_f32_32x32x16_bf16 v[32:47], v[128:131], v[116:119], v[32:47]
	v_add_f32_e32 v64, v70, v104
	v_add_f32_e32 v64, v71, v64
	v_add_f32_e32 v64, v72, v64
	v_add_f32_e32 v64, v73, v64
	v_cvt_pk_bf16_f32 v126, v68, v69
	v_cvt_pk_bf16_f32 v127, v70, v71
	ds_read_b64_tr_b16 v[132:133], v182 offset:25600
	ds_read_b64_tr_b16 v[134:135], v182 offset:26112
	v_mfma_f32_32x32x16_bf16 v[80:95], v[164:167], v[108:111], v[80:95]
	v_add_f32_e32 v64, v74, v64
	v_add_f32_e32 v64, v75, v64
	v_add_f32_e32 v64, v76, v64
	v_add_f32_e32 v64, v77, v64
	v_cvt_pk_bf16_f32 v120, v72, v73
	v_cvt_pk_bf16_f32 v121, v74, v75
	ds_read_b64_tr_b16 v[128:129], v182 offset:29696
	ds_read_b64_tr_b16 v[130:131], v182 offset:30208
	v_mfma_f32_32x32x16_bf16 v[32:47], v[152:155], v[108:111], v[32:47]
	v_add_f32_e32 v64, v78, v64
	v_add_f32_e32 v64, v79, v64
	v_add_f32_e32 v64, v48, v64
	v_add_f32_e32 v64, v49, v64
	v_cvt_pk_bf16_f32 v122, v76, v77
	v_cvt_pk_bf16_f32 v123, v78, v79
	ds_read_b64_tr_b16 v[172:173], v182 offset:26624
	ds_read_b64_tr_b16 v[174:175], v182 offset:27136
	v_mfma_f32_32x32x16_bf16 v[80:95], v[160:163], v[100:103], v[80:95]
	v_add_f32_e32 v64, v50, v64
	v_add_f32_e32 v64, v51, v64
	v_add_f32_e32 v64, v52, v64
	v_add_f32_e32 v64, v53, v64
	v_cvt_pk_bf16_f32 v112, v48, v49
	v_cvt_pk_bf16_f32 v113, v50, v51
	ds_read_b64_tr_b16 v[168:169], v182 offset:30720
	ds_read_b64_tr_b16 v[170:171], v182 offset:31232
	v_mfma_f32_32x32x16_bf16 v[32:47], v[148:151], v[100:103], v[32:47]
	v_add_f32_e32 v48, v54, v64
	v_add_f32_e32 v48, v55, v48
	v_add_f32_e32 v48, v56, v48
	v_add_f32_e32 v48, v57, v48
	v_cvt_pk_bf16_f32 v114, v52, v53
	v_cvt_pk_bf16_f32 v115, v54, v55
	ds_read_b64_tr_b16 v[164:165], v182 offset:27648
	ds_read_b64_tr_b16 v[166:167], v182 offset:28160
	v_mfma_f32_32x32x16_bf16 v[80:95], v[156:159], v[96:99], v[80:95]
	v_add_f32_e32 v48, v58, v48
	v_add_f32_e32 v48, v59, v48
	v_add_f32_e32 v48, v60, v48
	v_add_f32_e32 v48, v61, v48
	v_cvt_pk_bf16_f32 v104, v56, v57
	v_cvt_pk_bf16_f32 v105, v58, v59
	ds_read_b64_tr_b16 v[160:161], v182 offset:31744
	ds_read_b64_tr_b16 v[162:163], v182 offset:32256
	v_mfma_f32_32x32x16_bf16 v[32:47], v[136:139], v[96:99], v[32:47]
	v_add_f32_e32 v48, v62, v48
	v_add_f32_e32 v48, v63, v48
	v_add_f32_e32 v48, 0, v48
	v_cvt_pk_bf16_f32 v106, v60, v61
	v_cvt_pk_bf16_f32 v107, v62, v63
	v_max_f32_e32 v49, v80, v81
	s_nop 3
	v_max3_f32 v50, v82, v83, v33
	v_max3_f32 v49, v49, v32, v34
	v_max3_f32 v49, v49, v35, v84
	v_max3_f32 v50, v50, v86, v87
	v_max3_f32 v49, v49, v85, v36
	v_max3_f32 v50, v50, v38, v39
	v_max3_f32 v49, v49, v37, v88
	v_max3_f32 v50, v50, v90, v91
	v_max3_f32 v49, v49, v89, v40
	v_max3_f32 v50, v50, v42, v43
	v_max3_f32 v49, v49, v41, v92
	v_max3_f32 v50, v50, v94, v95
	v_max3_f32 v49, v49, v93, v44
	v_max3_f32 v50, v50, v46, v47
	v_add_f32_e32 v222, v181, v48
	v_max3_f32 v48, v49, v45, v50
	v_mov_b32_e32 v49, v48
	s_nop 1
	v_permlane32_swap_b32_e32 v48, v49
	v_max_f32_e32 v49, v49, v49
	s_add_i32 m0, s28, s18
	v_max_f32_e32 v48, v48, v48
	global_load_lds_dwordx4 v[178:179], off
	s_add_i32 m0, s22, s19
	v_max_f32_e32 v48, v48, v49
	global_load_lds_dwordx4 v[176:177], off
	v_cmp_lt_f32_e32 vcc, s47, v48
	s_cmp_lg_u64 vcc, 0
	s_cselect_b64 s[6:7], -1, 0
	s_cbranch_vccnz .LBB0_159
